# P2 GEMM: first K-loop iteration peeled with C=0 MFMAs (no 128-instruction accumulator clear per tile) on top of attention bias direct-load and P4 load hoisting
# speedup vs baseline: 1.0153x; 1.0064x over previous
; #define PG8_STAGE(bufoff, gbase, voff) do { _Pragma("unroll") for (int _i = 0; _i < 2; ++_i) \
;         __builtin_amdgcn_global_load_lds((const unsigned*)((const char*)(gbase) + (voff)[_i]), (PG8_LAS unsigned*)(lds + (bufoff) + ldsw + _i * 8192), 16, 0, 0); } while (0)
; #define PG8_LDA(dst, b, h) do { _Pragma("unroll") for (int m = 0; m < 4; ++m) _Pragma("unroll") for (int k = 0; k < 2; ++k) dst[m][k] = *(const PG8_LAS bf16x8*)(lds + PG8_SA(b, h) + aoff + m * 2048 + k * 1024); } while (0)
; #define PG8_LDB(dst, b, h) do { _Pragma("unroll") for (int n = 0; n < 2; ++n) _Pragma("unroll") for (int k = 0; k < 2; ++k) dst[n][k] = *(const PG8_LAS bf16x8*)(lds + PG8_SB(b, h) + boff + n * 2048 + k * 1024); } while (0)
; #define PG8_MMA(ai, bj, At, Bt) do { __builtin_amdgcn_s_setprio(1); _Pragma("unroll") for (int m = 0; m < 4; ++m) _Pragma("unroll") for (int n = 0; n < 2; ++n) _Pragma("unroll") for (int k = 0; k < 2; ++k) \
;         acc[ai][bj][m][n] = __builtin_amdgcn_mfma_f32_16x16x32_bf16(Bt[n][k], At[m][k], acc[ai][bj][m][n], 0, 0, 0); __builtin_amdgcn_s_setprio(0); } while (0)
; #define PG8_WAIT_V(n) asm volatile("s_waitcnt vmcnt(" #n ")" ::: "memory")
; #define PG8_WAIT_L(n) asm volatile("s_waitcnt lgkmcnt(" #n ")" ::: "memory")
; #define PG8_BAR __builtin_amdgcn_s_barrier()
; #define PG8_SCHED __builtin_amdgcn_sched_barrier(0)
; template <class Epi, class Sched, bool ALIGN_EPI = false, bool SP2 = false>
; __device__ __forceinline__ void gemm_phase(PG8_LAS unsigned char* lds, const Gemm g, const Sched& S, const Epi& E) {
;     ...
;             PG8_LDB(B0, 0, 0); PG8_LDB(B1, 0, 1); PG8_SCHED; PG8_LDA(At, 0, 0); PG8_STAGE(PG8_SA(1, 1), a1 + hstep, voffA);
;             PG8_WAIT_V(8); PG8_WAIT_L(0); PG8_BAR; PG8_MMA(0, 0, At, B0); PG8_MMA(0, 1, At, B1); PG8_BAR; PG8_SCHED;
;             PG8_LDA(At, 0, 1); PG8_STAGE(PG8_SB(0, 0), b2, voffB); PG8_STAGE(PG8_SB(0, 1), b2 + hstep, voffB); PG8_STAGE(PG8_SA(0, 0), a2, voffA);
;             PG8_WAIT_V(8); PG8_WAIT_L(0); PG8_BAR; PG8_MMA(1, 0, At, B0); PG8_MMA(1, 1, At, B1); PG8_BAR; PG8_SCHED;
;     ...
; #pragma unroll
;         for (int a = 0; a < 2; ++a)
; #pragma unroll
;             for (int b = 0; b < 2; ++b)
; #pragma unroll
;                 for (int m = 0; m < 4; ++m)
; #pragma unroll
;                     for (int n = 0; n < 2; ++n) acc[a][b][m][n] = (f32x4){0.f, 0.f, 0.f, 0.f};
.LBB0_233:
	s_ashr_i32 s35, s34, 31
	s_lshl_b64 s[36:37], s[34:35], 19
	s_add_u32 s36, s49, s36
	s_addc_u32 s37, s50, s37
	s_and_b64 s[38:39], s[4:5], exec
	s_cselect_b32 s7, s37, s43
	s_cselect_b32 s35, s36, s42
	s_ashr_i32 s31, s30, 31
	s_lshl_b64 s[38:39], s[30:31], 19
	s_add_u32 s38, s33, s38
	s_addc_u32 s39, s48, s39
	s_and_b64 s[46:47], s[4:5], exec
	s_cselect_b32 s31, s39, s45
	s_cselect_b32 s77, s38, s44
	s_add_u32 s42, s42, 0x40080
	s_addc_u32 s43, s43, 0
	s_add_u32 s78, s44, 0x100
	s_addc_u32 s79, s45, 0
	s_mov_b32 s80, -2
	ds_read_b128 v[152:155], v176
	ds_read_b128 v[156:159], v176 offset:1024
	ds_read_b128 v[160:163], v176 offset:2048
	ds_read_b128 v[182:185], v176 offset:3072
	ds_read_b128 v[186:189], v177
	ds_read_b128 v[190:193], v177 offset:1024
	ds_read_b128 v[194:197], v177 offset:2048
	ds_read_b128 v[198:201], v177 offset:3072
	s_add_u32 s44, s42, 0xfffc0080
	s_addc_u32 s45, s43, -1
	s_cmp_eq_u32 s80, 12
	s_cselect_b32 s47, s7, s45
	s_cselect_b32 s46, s35, s44
	s_cselect_b32 s45, s31, s79
	s_cselect_b32 s44, s77, s78
	v_lshl_add_u64 v[234:235], s[42:43], 0, v[144:145]
	s_add_i32 m0, s41, 0xc000
	ds_read_b128 v[202:205], v178
	ds_read_b128 v[206:209], v178 offset:1024
	ds_read_b128 v[210:213], v178 offset:2048
	ds_read_b128 v[214:217], v178 offset:3072
	ds_read_b128 v[218:221], v178 offset:4096
	ds_read_b128 v[222:225], v178 offset:5120
	ds_read_b128 v[226:229], v178 offset:6144
	ds_read_b128 v[230:233], v178 offset:7168
	global_load_lds_dwordx4 v[234:235], off
	v_lshl_add_u64 v[234:235], s[42:43], 0, v[146:147]
	s_add_i32 m0, s41, 0xe000
	s_nop 0
	global_load_lds_dwordx4 v[234:235], off
	s_waitcnt vmcnt(8)
	s_waitcnt lgkmcnt(0)
	s_barrier
	s_setprio 1
	s_waitcnt lgkmcnt(0)
	v_mfma_f32_16x16x32_bf16 v[126:129], v[152:155], v[202:205], 0
	v_mfma_f32_16x16x32_bf16 v[122:125], v[160:163], v[202:205], 0
	v_mfma_f32_16x16x32_bf16 v[114:117], v[152:155], v[210:213], 0
	v_mfma_f32_16x16x32_bf16 v[110:113], v[160:163], v[210:213], 0
	v_mfma_f32_16x16x32_bf16 v[98:101], v[152:155], v[218:221], 0
	v_mfma_f32_16x16x32_bf16 v[94:97], v[160:163], v[218:221], 0
	v_mfma_f32_16x16x32_bf16 v[82:85], v[152:155], v[226:229], 0
	v_mfma_f32_16x16x32_bf16 v[78:81], v[160:163], v[226:229], 0
	v_mfma_f32_16x16x32_bf16 v[126:129], v[156:159], v[206:209], v[126:129]
	v_mfma_f32_16x16x32_bf16 v[122:125], v[182:185], v[206:209], v[122:125]
	v_mfma_f32_16x16x32_bf16 v[114:117], v[156:159], v[214:217], v[114:117]
	v_mfma_f32_16x16x32_bf16 v[110:113], v[182:185], v[214:217], v[110:113]
	v_mfma_f32_16x16x32_bf16 v[98:101], v[156:159], v[222:225], v[98:101]
	v_mfma_f32_16x16x32_bf16 v[94:97], v[182:185], v[222:225], v[94:97]
	v_mfma_f32_16x16x32_bf16 v[82:85], v[156:159], v[230:233], v[82:85]
	v_mfma_f32_16x16x32_bf16 v[78:81], v[182:185], v[230:233], v[78:81]
	s_setprio 0
	s_setprio 1
	v_mfma_f32_16x16x32_bf16 v[118:121], v[186:189], v[202:205], 0
	v_mfma_f32_16x16x32_bf16 v[106:109], v[194:197], v[202:205], 0
	v_mfma_f32_16x16x32_bf16 v[102:105], v[186:189], v[210:213], 0
	v_mfma_f32_16x16x32_bf16 v[90:93], v[194:197], v[210:213], 0
	v_mfma_f32_16x16x32_bf16 v[86:89], v[186:189], v[218:221], 0
	v_mfma_f32_16x16x32_bf16 v[74:77], v[194:197], v[218:221], 0
	v_mfma_f32_16x16x32_bf16 v[70:73], v[186:189], v[226:229], 0
	v_mfma_f32_16x16x32_bf16 v[66:69], v[194:197], v[226:229], 0
	v_mfma_f32_16x16x32_bf16 v[118:121], v[190:193], v[206:209], v[118:121]
	v_mfma_f32_16x16x32_bf16 v[106:109], v[198:201], v[206:209], v[106:109]
	v_mfma_f32_16x16x32_bf16 v[102:105], v[190:193], v[214:217], v[102:105]
	v_mfma_f32_16x16x32_bf16 v[90:93], v[198:201], v[214:217], v[90:93]
	v_mfma_f32_16x16x32_bf16 v[86:89], v[190:193], v[222:225], v[86:89]
	v_mfma_f32_16x16x32_bf16 v[74:77], v[198:201], v[222:225], v[74:77]
	v_mfma_f32_16x16x32_bf16 v[70:73], v[190:193], v[230:233], v[70:73]
	v_mfma_f32_16x16x32_bf16 v[66:69], v[198:201], v[230:233], v[66:69]
	s_setprio 0
	s_barrier
	s_add_i32 s81, s64, s15
	v_lshl_add_u64 v[234:235], s[44:45], 0, v[132:133]
	s_mov_b32 m0, s81
	ds_read_b128 v[202:205], v178 offset:16384
	ds_read_b128 v[206:209], v178 offset:17408
	ds_read_b128 v[210:213], v178 offset:18432
	ds_read_b128 v[214:217], v178 offset:19456
	ds_read_b128 v[218:221], v178 offset:20480
	ds_read_b128 v[222:225], v178 offset:21504
	ds_read_b128 v[226:229], v178 offset:22528
	ds_read_b128 v[230:233], v178 offset:23552
	global_load_lds_dwordx4 v[234:235], off
	s_add_i32 m0, s81, 0x2000
	s_add_u32 s82, s44, 0x40000
	v_lshl_add_u64 v[236:237], s[44:45], 0, v[136:137]
	s_addc_u32 s83, s45, 0
	s_add_i32 s81, s65, s15
	global_load_lds_dwordx4 v[236:237], off
	v_lshl_add_u64 v[238:239], s[82:83], 0, v[132:133]
	s_mov_b32 m0, s81
	v_lshl_add_u64 v[240:241], s[46:47], 0, v[134:135]
	global_load_lds_dwordx4 v[238:239], off
	v_lshl_add_u64 v[238:239], s[82:83], 0, v[136:137]
	s_add_i32 m0, s81, 0x2000
	s_nop 0
	global_load_lds_dwordx4 v[238:239], off
	v_lshl_add_u64 v[238:239], s[46:47], 0, v[130:131]
	s_mov_b32 m0, s41
	s_nop 0
	global_load_lds_dwordx4 v[238:239], off
	s_mov_b32 m0, s51
	s_nop 0
	global_load_lds_dwordx4 v[240:241], off
	s_waitcnt vmcnt(8)
	s_waitcnt lgkmcnt(0)
	s_barrier
; #define PG8_STAGE(bufoff, gbase, voff) do { _Pragma("unroll") for (int _i = 0; _i < 2; ++_i) \
;         __builtin_amdgcn_global_load_lds((const unsigned*)((const char*)(gbase) + (voff)[_i]), (PG8_LAS unsigned*)(lds + (bufoff) + ldsw + _i * 8192), 16, 0, 0); } while (0)
; #define PG8_LDA(dst, b, h) do { _Pragma("unroll") for (int m = 0; m < 4; ++m) _Pragma("unroll") for (int k = 0; k < 2; ++k) dst[m][k] = *(const PG8_LAS bf16x8*)(lds + PG8_SA(b, h) + aoff + m * 2048 + k * 1024); } while (0)
; #define PG8_LDB(dst, b, h) do { _Pragma("unroll") for (int n = 0; n < 2; ++n) _Pragma("unroll") for (int k = 0; k < 2; ++k) dst[n][k] = *(const PG8_LAS bf16x8*)(lds + PG8_SB(b, h) + boff + n * 2048 + k * 1024); } while (0)
; #define PG8_MMA(ai, bj, At, Bt) do { __builtin_amdgcn_s_setprio(1); _Pragma("unroll") for (int m = 0; m < 4; ++m) _Pragma("unroll") for (int n = 0; n < 2; ++n) _Pragma("unroll") for (int k = 0; k < 2; ++k) \
;         acc[ai][bj][m][n] = __builtin_amdgcn_mfma_f32_16x16x32_bf16(Bt[n][k], At[m][k], acc[ai][bj][m][n], 0, 0, 0); __builtin_amdgcn_s_setprio(0); } while (0)
; #define PG8_WAIT_V(n) asm volatile("s_waitcnt vmcnt(" #n ")" ::: "memory")
; #define PG8_WAIT_L(n) asm volatile("s_waitcnt lgkmcnt(" #n ")" ::: "memory")
; #define PG8_BAR __builtin_amdgcn_s_barrier()
; #define PG8_SCHED __builtin_amdgcn_sched_barrier(0)
; template <class Epi, class Sched, bool ALIGN_EPI = false, bool SP2 = false>
; __device__ __forceinline__ void gemm_phase(PG8_LAS unsigned char* lds, const Gemm g, const Sched& S, const Epi& E) {
;     ...
;             PG8_WAIT_V(8); PG8_WAIT_L(0); PG8_BAR; PG8_MMA(1, 0, At, B0); PG8_MMA(1, 1, At, B1); PG8_BAR; PG8_SCHED;
;             PG8_LDB(B0, 1, 0); PG8_LDB(B1, 1, 1); PG8_SCHED; PG8_LDA(At, 1, 0); PG8_STAGE(PG8_SA(0, 1), a2 + hstep, voffA);
;             PG8_WAIT_V(8); PG8_WAIT_L(0); PG8_BAR; PG8_MMA(0, 0, At, B0); PG8_MMA(0, 1, At, B1); PG8_BAR; PG8_SCHED;
	s_setprio 1
	s_waitcnt lgkmcnt(0)
	v_mfma_f32_16x16x32_bf16 v[62:65], v[152:155], v[202:205], 0
	v_mfma_f32_16x16x32_bf16 v[58:61], v[160:163], v[202:205], 0
	v_mfma_f32_16x16x32_bf16 v[50:53], v[152:155], v[210:213], 0
	v_mfma_f32_16x16x32_bf16 v[46:49], v[160:163], v[210:213], 0
	v_mfma_f32_16x16x32_bf16 v[34:37], v[152:155], v[218:221], 0
	v_mfma_f32_16x16x32_bf16 v[30:33], v[160:163], v[218:221], 0
	v_mfma_f32_16x16x32_bf16 v[18:21], v[152:155], v[226:229], 0
	v_mfma_f32_16x16x32_bf16 v[14:17], v[160:163], v[226:229], 0
	v_mfma_f32_16x16x32_bf16 v[62:65], v[156:159], v[206:209], v[62:65]
	v_mfma_f32_16x16x32_bf16 v[58:61], v[182:185], v[206:209], v[58:61]
	v_mfma_f32_16x16x32_bf16 v[50:53], v[156:159], v[214:217], v[50:53]
	v_mfma_f32_16x16x32_bf16 v[46:49], v[182:185], v[214:217], v[46:49]
	v_mfma_f32_16x16x32_bf16 v[34:37], v[156:159], v[222:225], v[34:37]
	v_mfma_f32_16x16x32_bf16 v[30:33], v[182:185], v[222:225], v[30:33]
	v_mfma_f32_16x16x32_bf16 v[18:21], v[156:159], v[230:233], v[18:21]
	v_mfma_f32_16x16x32_bf16 v[14:17], v[182:185], v[230:233], v[14:17]
	s_setprio 0
	s_setprio 1
	v_mfma_f32_16x16x32_bf16 v[54:57], v[186:189], v[202:205], 0
	v_mfma_f32_16x16x32_bf16 v[42:45], v[194:197], v[202:205], 0
	v_mfma_f32_16x16x32_bf16 v[38:41], v[186:189], v[210:213], 0
	v_mfma_f32_16x16x32_bf16 v[26:29], v[194:197], v[210:213], 0
	v_mfma_f32_16x16x32_bf16 v[22:25], v[186:189], v[218:221], 0
	v_mfma_f32_16x16x32_bf16 v[10:13], v[194:197], v[218:221], 0
	v_mfma_f32_16x16x32_bf16 v[6:9], v[186:189], v[226:229], 0
	v_mfma_f32_16x16x32_bf16 v[2:5], v[194:197], v[226:229], 0
	v_mfma_f32_16x16x32_bf16 v[54:57], v[190:193], v[206:209], v[54:57]
	v_mfma_f32_16x16x32_bf16 v[42:45], v[198:201], v[206:209], v[42:45]
	v_mfma_f32_16x16x32_bf16 v[38:41], v[190:193], v[214:217], v[38:41]
	v_mfma_f32_16x16x32_bf16 v[26:29], v[198:201], v[214:217], v[26:29]
	v_mfma_f32_16x16x32_bf16 v[22:25], v[190:193], v[222:225], v[22:25]
	v_mfma_f32_16x16x32_bf16 v[10:13], v[198:201], v[222:225], v[10:13]
	v_mfma_f32_16x16x32_bf16 v[6:9], v[190:193], v[230:233], v[6:9]
	v_mfma_f32_16x16x32_bf16 v[2:5], v[198:201], v[230:233], v[2:5]
	s_setprio 0
	s_barrier
	s_add_i32 s81, 0, 0x18000
	v_add_u32_e32 v138, s81, v172
	s_add_i32 s82, 0, 0x1c000
	ds_read_b128 v[152:155], v138
	ds_read_b128 v[156:159], v138 offset:1024
	ds_read_b128 v[160:163], v138 offset:2048
	ds_read_b128 v[182:185], v138 offset:3072
	v_add_u32_e32 v138, s82, v172
	ds_read_b128 v[186:189], v138
	ds_read_b128 v[190:193], v138 offset:1024
	ds_read_b128 v[194:197], v138 offset:2048
	ds_read_b128 v[198:201], v138 offset:3072
	s_add_u32 s46, s46, 0x40000
	s_addc_u32 s47, s47, 0
	s_mov_b32 m0, s52
	v_lshl_add_u64 v[242:243], s[46:47], 0, v[130:131]
	ds_read_b128 v[202:205], v178 offset:32768
	ds_read_b128 v[206:209], v178 offset:33792
	ds_read_b128 v[210:213], v178 offset:34816
	ds_read_b128 v[214:217], v178 offset:35840
	ds_read_b128 v[218:221], v178 offset:36864
	ds_read_b128 v[222:225], v178 offset:37888
	ds_read_b128 v[226:229], v178 offset:38912
	ds_read_b128 v[230:233], v178 offset:39936
	global_load_lds_dwordx4 v[242:243], off
	v_lshl_add_u64 v[242:243], s[46:47], 0, v[134:135]
	s_mov_b32 m0, s53
	s_nop 0
	global_load_lds_dwordx4 v[242:243], off
	s_waitcnt vmcnt(8)
	s_waitcnt lgkmcnt(0)
	s_barrier
	s_setprio 1
	s_waitcnt lgkmcnt(0)
	v_mfma_f32_16x16x32_bf16 v[126:129], v[152:155], v[202:205], v[126:129]
	v_mfma_f32_16x16x32_bf16 v[122:125], v[160:163], v[202:205], v[122:125]
	v_mfma_f32_16x16x32_bf16 v[114:117], v[152:155], v[210:213], v[114:117]
	v_mfma_f32_16x16x32_bf16 v[110:113], v[160:163], v[210:213], v[110:113]
	v_mfma_f32_16x16x32_bf16 v[98:101], v[152:155], v[218:221], v[98:101]
	v_mfma_f32_16x16x32_bf16 v[94:97], v[160:163], v[218:221], v[94:97]
	v_mfma_f32_16x16x32_bf16 v[82:85], v[152:155], v[226:229], v[82:85]
	v_mfma_f32_16x16x32_bf16 v[78:81], v[160:163], v[226:229], v[78:81]
	v_mfma_f32_16x16x32_bf16 v[126:129], v[156:159], v[206:209], v[126:129]
	v_mfma_f32_16x16x32_bf16 v[122:125], v[182:185], v[206:209], v[122:125]
	v_mfma_f32_16x16x32_bf16 v[114:117], v[156:159], v[214:217], v[114:117]
	v_mfma_f32_16x16x32_bf16 v[110:113], v[182:185], v[214:217], v[110:113]
	v_mfma_f32_16x16x32_bf16 v[98:101], v[156:159], v[222:225], v[98:101]
	v_mfma_f32_16x16x32_bf16 v[94:97], v[182:185], v[222:225], v[94:97]
	v_mfma_f32_16x16x32_bf16 v[82:85], v[156:159], v[230:233], v[82:85]
	v_mfma_f32_16x16x32_bf16 v[78:81], v[182:185], v[230:233], v[78:81]
	s_setprio 0
	s_setprio 1
	v_mfma_f32_16x16x32_bf16 v[118:121], v[186:189], v[202:205], v[118:121]
	v_mfma_f32_16x16x32_bf16 v[106:109], v[194:197], v[202:205], v[106:109]
	v_mfma_f32_16x16x32_bf16 v[102:105], v[186:189], v[210:213], v[102:105]
	v_mfma_f32_16x16x32_bf16 v[90:93], v[194:197], v[210:213], v[90:93]
	v_mfma_f32_16x16x32_bf16 v[86:89], v[186:189], v[218:221], v[86:89]
	v_mfma_f32_16x16x32_bf16 v[74:77], v[194:197], v[218:221], v[74:77]
	v_mfma_f32_16x16x32_bf16 v[70:73], v[186:189], v[226:229], v[70:73]
	v_mfma_f32_16x16x32_bf16 v[66:69], v[194:197], v[226:229], v[66:69]
	v_mfma_f32_16x16x32_bf16 v[118:121], v[190:193], v[206:209], v[118:121]
	v_mfma_f32_16x16x32_bf16 v[106:109], v[198:201], v[206:209], v[106:109]
	v_mfma_f32_16x16x32_bf16 v[102:105], v[190:193], v[214:217], v[102:105]
	v_mfma_f32_16x16x32_bf16 v[90:93], v[198:201], v[214:217], v[90:93]
	v_mfma_f32_16x16x32_bf16 v[86:89], v[190:193], v[222:225], v[86:89]
	v_mfma_f32_16x16x32_bf16 v[74:77], v[198:201], v[222:225], v[74:77]
	v_mfma_f32_16x16x32_bf16 v[70:73], v[190:193], v[230:233], v[70:73]
	v_mfma_f32_16x16x32_bf16 v[66:69], v[198:201], v[230:233], v[66:69]
	s_setprio 0
	s_barrier
; #define PG8_STAGE(bufoff, gbase, voff) do { _Pragma("unroll") for (int _i = 0; _i < 2; ++_i) \
;         __builtin_amdgcn_global_load_lds((const unsigned*)((const char*)(gbase) + (voff)[_i]), (PG8_LAS unsigned*)(lds + (bufoff) + ldsw + _i * 8192), 16, 0, 0); } while (0)
; #define PG8_LDA(dst, b, h) do { _Pragma("unroll") for (int m = 0; m < 4; ++m) _Pragma("unroll") for (int k = 0; k < 2; ++k) dst[m][k] = *(const PG8_LAS bf16x8*)(lds + PG8_SA(b, h) + aoff + m * 2048 + k * 1024); } while (0)
; #define PG8_MMA(ai, bj, At, Bt) do { __builtin_amdgcn_s_setprio(1); _Pragma("unroll") for (int m = 0; m < 4; ++m) _Pragma("unroll") for (int n = 0; n < 2; ++n) _Pragma("unroll") for (int k = 0; k < 2; ++k) \
;         acc[ai][bj][m][n] = __builtin_amdgcn_mfma_f32_16x16x32_bf16(Bt[n][k], At[m][k], acc[ai][bj][m][n], 0, 0, 0); __builtin_amdgcn_s_setprio(0); } while (0)
; #define PG8_WAIT_V(n) asm volatile("s_waitcnt vmcnt(" #n ")" ::: "memory")
; #define PG8_WAIT_L(n) asm volatile("s_waitcnt lgkmcnt(" #n ")" ::: "memory")
; #define PG8_BAR __builtin_amdgcn_s_barrier()
; #define PG8_SCHED __builtin_amdgcn_sched_barrier(0)
; template <class Epi, class Sched, bool ALIGN_EPI = false, bool SP2 = false>
; __device__ __forceinline__ void gemm_phase(PG8_LAS unsigned char* lds, const Gemm g, const Sched& S, const Epi& E) {
;     ...
;         for (int t = 0; t < nt; t += 2) {
;             if constexpr (Epi::MID) { if (t == nt / 2) E.mid(acc, cur, wr, wc, fr, fq); }
;             const bool last = (t == nt - 2);
;             const char* a1 = cA + (size_t)(t + 1) * kstep;
;             const char* a2 = last ? nA : cA + (size_t)(t + 2) * kstep; const char* b2 = last ? nB : cB + (size_t)(t + 2) * kstep;
;             const char* a3 = a2 + kstep; const char* b3 = b2 + kstep;
;     ...
;             PG8_LDA(At, 1, 1); PG8_STAGE(PG8_SB(1, 0), b3, voffB); PG8_STAGE(PG8_SB(1, 1), b3 + hstep, voffB); PG8_STAGE(PG8_SA(1, 0), a3, voffA);
;             PG8_WAIT_V(8); PG8_WAIT_L(0); PG8_BAR; PG8_MMA(1, 0, At, B0); PG8_MMA(1, 1, At, B1); PG8_BAR; PG8_SCHED;
	s_add_i32 s46, s81, s15
	v_lshl_add_u64 v[234:235], v[234:235], 0, s[20:21]
	s_mov_b32 m0, s46
	ds_read_b128 v[202:205], v178 offset:49152
	ds_read_b128 v[206:209], v178 offset:50176
	ds_read_b128 v[210:213], v178 offset:51200
	ds_read_b128 v[214:217], v178 offset:52224
	ds_read_b128 v[218:221], v178 offset:53248
	ds_read_b128 v[222:225], v178 offset:54272
	ds_read_b128 v[226:229], v178 offset:55296
	ds_read_b128 v[230:233], v178 offset:56320
	global_load_lds_dwordx4 v[234:235], off
	s_add_i32 m0, s46, 0x2000
	s_add_u32 s44, s44, 0x40080
	v_lshl_add_u64 v[234:235], v[236:237], 0, s[20:21]
	s_addc_u32 s45, s45, 0
	s_add_i32 s46, s82, s15
	global_load_lds_dwordx4 v[234:235], off
	v_lshl_add_u64 v[234:235], s[44:45], 0, v[132:133]
	s_mov_b32 m0, s46
	s_nop 0
	global_load_lds_dwordx4 v[234:235], off
	v_lshl_add_u64 v[234:235], s[44:45], 0, v[136:137]
	s_add_i32 m0, s46, 0x2000
	s_nop 0
	global_load_lds_dwordx4 v[234:235], off
	v_lshl_add_u64 v[234:235], v[238:239], 0, s[20:21]
	s_mov_b32 m0, s57
	s_nop 0
	global_load_lds_dwordx4 v[234:235], off
	v_lshl_add_u64 v[234:235], v[240:241], 0, s[20:21]
	s_mov_b32 m0, s58
	s_nop 0
	global_load_lds_dwordx4 v[234:235], off
	s_waitcnt vmcnt(8)
	s_waitcnt lgkmcnt(0)
	s_barrier
	s_setprio 1
	s_waitcnt lgkmcnt(0)
	v_mfma_f32_16x16x32_bf16 v[62:65], v[152:155], v[202:205], v[62:65]
	v_mfma_f32_16x16x32_bf16 v[58:61], v[160:163], v[202:205], v[58:61]
	v_mfma_f32_16x16x32_bf16 v[50:53], v[152:155], v[210:213], v[50:53]
	v_mfma_f32_16x16x32_bf16 v[46:49], v[160:163], v[210:213], v[46:49]
	v_mfma_f32_16x16x32_bf16 v[34:37], v[152:155], v[218:221], v[34:37]
	v_mfma_f32_16x16x32_bf16 v[30:33], v[160:163], v[218:221], v[30:33]
	v_mfma_f32_16x16x32_bf16 v[18:21], v[152:155], v[226:229], v[18:21]
	v_mfma_f32_16x16x32_bf16 v[14:17], v[160:163], v[226:229], v[14:17]
	v_mfma_f32_16x16x32_bf16 v[62:65], v[156:159], v[206:209], v[62:65]
	v_mfma_f32_16x16x32_bf16 v[58:61], v[182:185], v[206:209], v[58:61]
	v_mfma_f32_16x16x32_bf16 v[50:53], v[156:159], v[214:217], v[50:53]
	v_mfma_f32_16x16x32_bf16 v[46:49], v[182:185], v[214:217], v[46:49]
	v_mfma_f32_16x16x32_bf16 v[34:37], v[156:159], v[222:225], v[34:37]
	v_mfma_f32_16x16x32_bf16 v[30:33], v[182:185], v[222:225], v[30:33]
	v_mfma_f32_16x16x32_bf16 v[18:21], v[156:159], v[230:233], v[18:21]
	v_mfma_f32_16x16x32_bf16 v[14:17], v[182:185], v[230:233], v[14:17]
	s_setprio 0
	s_setprio 1
	v_mfma_f32_16x16x32_bf16 v[54:57], v[186:189], v[202:205], v[54:57]
	v_mfma_f32_16x16x32_bf16 v[42:45], v[194:197], v[202:205], v[42:45]
	v_mfma_f32_16x16x32_bf16 v[38:41], v[186:189], v[210:213], v[38:41]
	v_mfma_f32_16x16x32_bf16 v[26:29], v[194:197], v[210:213], v[26:29]
	v_mfma_f32_16x16x32_bf16 v[22:25], v[186:189], v[218:221], v[22:25]
	v_mfma_f32_16x16x32_bf16 v[10:13], v[194:197], v[218:221], v[10:13]
	v_mfma_f32_16x16x32_bf16 v[6:9], v[186:189], v[226:229], v[6:9]
	v_mfma_f32_16x16x32_bf16 v[2:5], v[194:197], v[226:229], v[2:5]
	v_mfma_f32_16x16x32_bf16 v[54:57], v[190:193], v[206:209], v[54:57]
	v_mfma_f32_16x16x32_bf16 v[42:45], v[198:201], v[206:209], v[42:45]
	v_mfma_f32_16x16x32_bf16 v[38:41], v[190:193], v[214:217], v[38:41]
	v_mfma_f32_16x16x32_bf16 v[26:29], v[198:201], v[214:217], v[26:29]
	v_mfma_f32_16x16x32_bf16 v[22:25], v[190:193], v[222:225], v[22:25]
	v_mfma_f32_16x16x32_bf16 v[10:13], v[198:201], v[222:225], v[10:13]
	v_mfma_f32_16x16x32_bf16 v[6:9], v[190:193], v[230:233], v[6:9]
	v_mfma_f32_16x16x32_bf16 v[2:5], v[198:201], v[230:233], v[2:5]
	s_setprio 0
	s_barrier
	s_add_i32 s80, s80, 2
	s_add_u32 s42, s42, 0x100
	s_addc_u32 s43, s43, 0
	s_add_u32 s78, s78, 0x100
	s_addc_u32 s79, s79, 0
	s_cmp_gt_u32 s80, 13
